# GEMM-1 K loop hand-written: operand tiles HBM->LDS by global_load_lds (no staging VGPRs / ds_write), two swizzled LDS stages, one barrier per K step; static LDS 71744
# speedup vs baseline: 1.0659x; 1.0270x over previous
; DEV int tid_() { int t = threadIdx.x; asm volatile("" : "+v"(t)); return t; }
; DEV int bid_() { int b = blockIdx.x; asm volatile("" : "+s"(b)); return b; }
; template <int NI, bool DEEP = true>
; DEV void gemm_tile(f32x16 (&acc)[2][NI], const bf16* __restrict__ A, int lda, const bf16* __restrict__ Bt, int ldb,
;                    int K, bf16* sA, bf16* sB) {
;   int tid = tid_(), lane = tid & 63, wave = tid >> 6;
;   int wm = wave >> 1, wn = wave & 1;
;   int lr = tid >> 3, lc = (tid & 7) * 8;
;   const bf16* Ap = A + (size_t)lr * lda + lc;
;   const bf16* Bp = Bt + (size_t)lr * ldb + lc;
;   u32x4 ra0[4], rb0[2 * NI], ra1[4], rb1[2 * NI];
; __device__ void phase_gemm1(PRef p, bf16* sA, bf16* sB) {
;   const int xcd_ = bid_() & 7, per_ = gridDim.x >> 3;
;   for (int t = bid_() >> 3; t < 36 * 24; t += per_) {
;     int rt = xcd_ + 8 * (t / 24), ct = t % 24;
;     f32x16 acc[2][2];
;     zero_acc<2>(acc);
;     gemm_tile<2>(acc, p.HY + (size_t)rt * 128 * 1024, 1024, p.WT1 + (size_t)ct * 128 * 1024, 1024, 1024, sA, sB);
.LBB0_305:
	s_mul_hi_i32 s0, s24, 0x2aaaaaab
	s_lshr_b32 s1, s0, 31
	s_ashr_i32 s0, s0, 2
	s_add_i32 s0, s0, s1
	s_lshl_b32 s1, s0, 3
	s_or_b32 s10, s1, s25
	s_mul_i32 s0, s0, 24
	s_sub_i32 s12, s24, s0
	v_and_b32_e32 v0, 63, v196
	v_lshrrev_b32_e32 v1, 6, v196
	v_lshrrev_b32_e32 v2, 3, v0
	v_readfirstlane_b32 s16, v1
	v_lshrrev_b32_e32 v78, 1, v2
	v_and_b32_e32 v79, 7, v0
	v_xor_b32_e32 v78, v79, v78
	v_lshlrev_b32_e32 v78, 4, v78
	v_lshl_or_b32 v68, v2, 11, v78
	v_xor_b32_e32 v69, 64, v68
	v_lshrrev_b32_e32 v78, 5, v0
	v_bfe_u32 v79, v0, 1, 3
	v_and_b32_e32 v2, 31, v0
	v_lshrrev_b32_e32 v0, 1, v1
	v_and_b32_e32 v1, 1, v1
	v_lshl_add_u32 v0, v0, 6, v2
	v_lshl_add_u32 v1, v1, 6, v2
	v_lshlrev_b32_e32 v0, 7, v0
	v_lshlrev_b32_e32 v1, 7, v1
	v_add_u32_e32 v1, 0x4000, v1
	v_add_u32_e32 v2, 0, v78
	v_xor_b32_e32 v2, v2, v79
	v_lshl_add_u32 v70, v2, 4, v0
	v_lshl_add_u32 v74, v2, 4, v1
	v_add_u32_e32 v2, 2, v78
	v_xor_b32_e32 v2, v2, v79
	v_lshl_add_u32 v71, v2, 4, v0
	v_lshl_add_u32 v75, v2, 4, v1
	v_add_u32_e32 v2, 4, v78
	v_xor_b32_e32 v2, v2, v79
	v_lshl_add_u32 v72, v2, 4, v0
	v_lshl_add_u32 v76, v2, 4, v1
	v_add_u32_e32 v2, 6, v78
	v_xor_b32_e32 v2, v2, v79
	v_lshl_add_u32 v73, v2, 4, v0
	v_lshl_add_u32 v77, v2, 4, v1
	s_lshl_b32 s17, s16, 16
	s_lshl_b32 s16, s16, 12
	s_lshl_b32 s0, s10, 18
	s_add_u32 s98, s86, s0
	s_addc_u32 s99, s87, 0
	s_add_u32 s98, s98, s17
	s_addc_u32 s99, s99, 0
	s_lshl_b32 s0, s12, 18
	s_waitcnt lgkmcnt(0)
	s_add_u32 s100, s4, s0
	s_addc_u32 s101, s5, 0
	s_add_u32 s100, s100, s17
	s_addc_u32 s101, s101, 0
	s_barrier
	s_add_u32 m0, s16, 0x0
	s_nop 0
	global_load_lds_dwordx4 v68, s[98:99]
	s_add_u32 m0, s16, 0x400
	s_add_u32 s14, s98, 0x4000
	s_addc_u32 s15, s99, 0
	global_load_lds_dwordx4 v69, s[14:15]
	s_add_u32 m0, s16, 0x800
	s_add_u32 s14, s98, 0x8000
	s_addc_u32 s15, s99, 0
	global_load_lds_dwordx4 v68, s[14:15]
	s_add_u32 m0, s16, 0xc00
	s_add_u32 s14, s98, 0xc000
	s_addc_u32 s15, s99, 0
	global_load_lds_dwordx4 v69, s[14:15]
	s_add_u32 m0, s16, 0x4000
	s_nop 0
	global_load_lds_dwordx4 v68, s[100:101]
	s_add_u32 m0, s16, 0x4400
	s_add_u32 s14, s100, 0x4000
	s_addc_u32 s15, s101, 0
	global_load_lds_dwordx4 v69, s[14:15]
	s_add_u32 m0, s16, 0x4800
	s_add_u32 s14, s100, 0x8000
	s_addc_u32 s15, s101, 0
	global_load_lds_dwordx4 v68, s[14:15]
	s_add_u32 m0, s16, 0x4c00
	s_add_u32 s14, s100, 0xc000
	s_addc_u32 s15, s101, 0
	global_load_lds_dwordx4 v69, s[14:15]
	s_add_u32 s98, s98, 0x80
	s_addc_u32 s99, s99, 0
	s_add_u32 s100, s100, 0x80
	s_addc_u32 s101, s101, 0
	v_mov_b32_e32 v4, 0
	v_mov_b32_e32 v5, 0
	v_mov_b32_e32 v6, 0
	v_mov_b32_e32 v7, 0
	v_mov_b32_e32 v8, 0
	v_mov_b32_e32 v9, 0
	v_mov_b32_e32 v10, 0
	v_mov_b32_e32 v11, 0
	v_mov_b32_e32 v12, 0
	v_mov_b32_e32 v13, 0
	v_mov_b32_e32 v14, 0
	v_mov_b32_e32 v15, 0
	v_mov_b32_e32 v16, 0
	v_mov_b32_e32 v17, 0
	v_mov_b32_e32 v18, 0
	v_mov_b32_e32 v19, 0
	v_mov_b32_e32 v20, 0
	v_mov_b32_e32 v21, 0
	v_mov_b32_e32 v22, 0
	v_mov_b32_e32 v23, 0
	v_mov_b32_e32 v24, 0
	v_mov_b32_e32 v25, 0
	v_mov_b32_e32 v26, 0
	v_mov_b32_e32 v27, 0
	v_mov_b32_e32 v28, 0
	v_mov_b32_e32 v29, 0
	v_mov_b32_e32 v30, 0
	v_mov_b32_e32 v31, 0
	v_mov_b32_e32 v32, 0
	v_mov_b32_e32 v33, 0
	v_mov_b32_e32 v34, 0
	v_mov_b32_e32 v35, 0
	v_mov_b32_e32 v36, 0
	v_mov_b32_e32 v37, 0
	v_mov_b32_e32 v38, 0
	v_mov_b32_e32 v39, 0
	v_mov_b32_e32 v40, 0
	v_mov_b32_e32 v41, 0
	v_mov_b32_e32 v42, 0
	v_mov_b32_e32 v43, 0
	v_mov_b32_e32 v44, 0
	v_mov_b32_e32 v45, 0
	v_mov_b32_e32 v46, 0
	v_mov_b32_e32 v47, 0
	v_mov_b32_e32 v48, 0
	v_mov_b32_e32 v49, 0
	v_mov_b32_e32 v50, 0
	v_mov_b32_e32 v51, 0
	v_mov_b32_e32 v52, 0
	v_mov_b32_e32 v53, 0
	v_mov_b32_e32 v54, 0
	v_mov_b32_e32 v55, 0
	v_mov_b32_e32 v56, 0
	v_mov_b32_e32 v57, 0
	v_mov_b32_e32 v58, 0
	v_mov_b32_e32 v59, 0
	v_mov_b32_e32 v60, 0
	v_mov_b32_e32 v61, 0
	v_mov_b32_e32 v62, 0
	v_mov_b32_e32 v63, 0
	v_mov_b32_e32 v64, 0
	v_mov_b32_e32 v65, 0
	v_mov_b32_e32 v66, 0
	v_mov_b32_e32 v67, 0
	s_mov_b32 s11, 0
; template <int NI, bool DEEP = true>
; DEV void gemm_tile(f32x16 (&acc)[2][NI], const bf16* __restrict__ A, int lda, const bf16* __restrict__ Bt, int ldb,
;                    int K, bf16* sA, bf16* sB) {
;     ...
;   G_LOAD(ra0, rb0, 0)
;   if (DEEP) {
;     if (64 < K) G_LOAD(ra1, rb1, 64)
;     for (int k0 = 0; k0 < K; k0 += 128) {
;       G_STEP(ra0, rb0, k0 + 128)
;       if (k0 + 64 < K) G_STEP(ra1, rb1, k0 + 192)
;     }
;   } else {
;     for (int k0 = 0; k0 < K; k0 += 64) G_STEP(ra0, rb0, k0 + 64)
;   }
.Lg1k_loop:
	s_waitcnt vmcnt(0)
	s_barrier
	s_add_u32 m0, s16, 0x8000
	s_nop 0
	global_load_lds_dwordx4 v68, s[98:99]
	s_add_u32 m0, s16, 0x8400
	s_add_u32 s14, s98, 0x4000
	s_addc_u32 s15, s99, 0
	global_load_lds_dwordx4 v69, s[14:15]
	s_add_u32 m0, s16, 0x8800
	s_add_u32 s14, s98, 0x8000
	s_addc_u32 s15, s99, 0
	global_load_lds_dwordx4 v68, s[14:15]
	s_add_u32 m0, s16, 0x8c00
	s_add_u32 s14, s98, 0xc000
	s_addc_u32 s15, s99, 0
	global_load_lds_dwordx4 v69, s[14:15]
	s_add_u32 m0, s16, 0xd840
	s_nop 0
	global_load_lds_dwordx4 v68, s[100:101]
	s_add_u32 m0, s16, 0xdc40
	s_add_u32 s14, s100, 0x4000
	s_addc_u32 s15, s101, 0
	global_load_lds_dwordx4 v69, s[14:15]
	s_add_u32 m0, s16, 0xe040
	s_add_u32 s14, s100, 0x8000
	s_addc_u32 s15, s101, 0
	global_load_lds_dwordx4 v68, s[14:15]
	s_add_u32 m0, s16, 0xe440
	s_add_u32 s14, s100, 0xc000
	s_addc_u32 s15, s101, 0
	global_load_lds_dwordx4 v69, s[14:15]
	s_add_u32 s98, s98, 0x80
	s_addc_u32 s99, s99, 0
	s_add_u32 s100, s100, 0x80
	s_addc_u32 s101, s101, 0
	ds_read_b128 v[88:91], v74 offset:0
	ds_read_b128 v[80:83], v70 offset:0
	ds_read_b128 v[84:87], v70 offset:4096
	ds_read_b128 v[92:95], v74 offset:4096
	s_waitcnt lgkmcnt(2)
	v_mfma_f32_32x32x16_bf16 v[52:67], v[88:91], v[80:83], v[52:67]
	ds_read_b128 v[104:107], v75 offset:0
	ds_read_b128 v[96:99], v71 offset:0
	s_waitcnt lgkmcnt(3)
	v_mfma_f32_32x32x16_bf16 v[20:35], v[88:91], v[84:87], v[20:35]
	ds_read_b128 v[100:103], v71 offset:4096
	s_waitcnt lgkmcnt(3)
	v_mfma_f32_32x32x16_bf16 v[36:51], v[92:95], v[80:83], v[36:51]
	ds_read_b128 v[108:111], v75 offset:4096
	v_mfma_f32_32x32x16_bf16 v[4:19], v[92:95], v[84:87], v[4:19]
	s_waitcnt lgkmcnt(2)
	v_mfma_f32_32x32x16_bf16 v[52:67], v[104:107], v[96:99], v[52:67]
	ds_read_b128 v[88:91], v76 offset:0
	ds_read_b128 v[80:83], v72 offset:0
	s_waitcnt lgkmcnt(3)
	v_mfma_f32_32x32x16_bf16 v[20:35], v[104:107], v[100:103], v[20:35]
	ds_read_b128 v[84:87], v72 offset:4096
	s_waitcnt lgkmcnt(3)
	v_mfma_f32_32x32x16_bf16 v[36:51], v[108:111], v[96:99], v[36:51]
	ds_read_b128 v[92:95], v76 offset:4096
	v_mfma_f32_32x32x16_bf16 v[4:19], v[108:111], v[100:103], v[4:19]
	s_waitcnt lgkmcnt(2)
	v_mfma_f32_32x32x16_bf16 v[52:67], v[88:91], v[80:83], v[52:67]
	ds_read_b128 v[104:107], v77 offset:0
	ds_read_b128 v[96:99], v73 offset:0
	s_waitcnt lgkmcnt(3)
	v_mfma_f32_32x32x16_bf16 v[20:35], v[88:91], v[84:87], v[20:35]
	ds_read_b128 v[100:103], v73 offset:4096
	s_waitcnt lgkmcnt(3)
	v_mfma_f32_32x32x16_bf16 v[36:51], v[92:95], v[80:83], v[36:51]
	ds_read_b128 v[108:111], v77 offset:4096
	v_mfma_f32_32x32x16_bf16 v[4:19], v[92:95], v[84:87], v[4:19]
	s_waitcnt lgkmcnt(2)
	v_mfma_f32_32x32x16_bf16 v[52:67], v[104:107], v[96:99], v[52:67]
	s_waitcnt lgkmcnt(1)
	v_mfma_f32_32x32x16_bf16 v[20:35], v[104:107], v[100:103], v[20:35]
	s_waitcnt lgkmcnt(0)
	v_mfma_f32_32x32x16_bf16 v[36:51], v[108:111], v[96:99], v[36:51]
	v_mfma_f32_32x32x16_bf16 v[4:19], v[108:111], v[100:103], v[4:19]
	s_waitcnt vmcnt(0)
	s_barrier
	s_cmp_eq_u32 s11, 7
	s_cbranch_scc1 .Lg1k_nodma
	s_add_u32 m0, s16, 0x0
	s_nop 0
	global_load_lds_dwordx4 v68, s[98:99]
	s_add_u32 m0, s16, 0x400
	s_add_u32 s14, s98, 0x4000
	s_addc_u32 s15, s99, 0
	global_load_lds_dwordx4 v69, s[14:15]
	s_add_u32 m0, s16, 0x800
	s_add_u32 s14, s98, 0x8000
	s_addc_u32 s15, s99, 0
	global_load_lds_dwordx4 v68, s[14:15]
	s_add_u32 m0, s16, 0xc00
	s_add_u32 s14, s98, 0xc000
	s_addc_u32 s15, s99, 0
	global_load_lds_dwordx4 v69, s[14:15]
	s_add_u32 m0, s16, 0x4000
	s_nop 0
	global_load_lds_dwordx4 v68, s[100:101]
	s_add_u32 m0, s16, 0x4400
	s_add_u32 s14, s100, 0x4000
	s_addc_u32 s15, s101, 0
	global_load_lds_dwordx4 v69, s[14:15]
	s_add_u32 m0, s16, 0x4800
	s_add_u32 s14, s100, 0x8000
	s_addc_u32 s15, s101, 0
	global_load_lds_dwordx4 v68, s[14:15]
	s_add_u32 m0, s16, 0x4c00
	s_add_u32 s14, s100, 0xc000
	s_addc_u32 s15, s101, 0
	global_load_lds_dwordx4 v69, s[14:15]
	s_add_u32 s98, s98, 0x80
	s_addc_u32 s99, s99, 0
	s_add_u32 s100, s100, 0x80
	s_addc_u32 s101, s101, 0
.Lg1k_nodma:
	ds_read_b128 v[88:91], v74 offset:38976
	ds_read_b128 v[80:83], v70 offset:32768
	ds_read_b128 v[84:87], v70 offset:36864
	ds_read_b128 v[92:95], v74 offset:43072
	s_waitcnt lgkmcnt(2)
	v_mfma_f32_32x32x16_bf16 v[52:67], v[88:91], v[80:83], v[52:67]
	ds_read_b128 v[104:107], v75 offset:38976
	ds_read_b128 v[96:99], v71 offset:32768
	s_waitcnt lgkmcnt(3)
	v_mfma_f32_32x32x16_bf16 v[20:35], v[88:91], v[84:87], v[20:35]
	ds_read_b128 v[100:103], v71 offset:36864
	s_waitcnt lgkmcnt(3)
	v_mfma_f32_32x32x16_bf16 v[36:51], v[92:95], v[80:83], v[36:51]
	ds_read_b128 v[108:111], v75 offset:43072
	v_mfma_f32_32x32x16_bf16 v[4:19], v[92:95], v[84:87], v[4:19]
	s_waitcnt lgkmcnt(2)
	v_mfma_f32_32x32x16_bf16 v[52:67], v[104:107], v[96:99], v[52:67]
	ds_read_b128 v[88:91], v76 offset:38976
	ds_read_b128 v[80:83], v72 offset:32768
	s_waitcnt lgkmcnt(3)
	v_mfma_f32_32x32x16_bf16 v[20:35], v[104:107], v[100:103], v[20:35]
	ds_read_b128 v[84:87], v72 offset:36864
	s_waitcnt lgkmcnt(3)
	v_mfma_f32_32x32x16_bf16 v[36:51], v[108:111], v[96:99], v[36:51]
	ds_read_b128 v[92:95], v76 offset:43072
	v_mfma_f32_32x32x16_bf16 v[4:19], v[108:111], v[100:103], v[4:19]
	s_waitcnt lgkmcnt(2)
	v_mfma_f32_32x32x16_bf16 v[52:67], v[88:91], v[80:83], v[52:67]
	ds_read_b128 v[104:107], v77 offset:38976
	ds_read_b128 v[96:99], v73 offset:32768
	s_waitcnt lgkmcnt(3)
	v_mfma_f32_32x32x16_bf16 v[20:35], v[88:91], v[84:87], v[20:35]
	ds_read_b128 v[100:103], v73 offset:36864
	s_waitcnt lgkmcnt(3)
	v_mfma_f32_32x32x16_bf16 v[36:51], v[92:95], v[80:83], v[36:51]
	ds_read_b128 v[108:111], v77 offset:43072
	v_mfma_f32_32x32x16_bf16 v[4:19], v[92:95], v[84:87], v[4:19]
	s_waitcnt lgkmcnt(2)
	v_mfma_f32_32x32x16_bf16 v[52:67], v[104:107], v[96:99], v[52:67]
	s_waitcnt lgkmcnt(1)
	v_mfma_f32_32x32x16_bf16 v[20:35], v[104:107], v[100:103], v[20:35]
	s_waitcnt lgkmcnt(0)
	v_mfma_f32_32x32x16_bf16 v[36:51], v[108:111], v[96:99], v[36:51]
	v_mfma_f32_32x32x16_bf16 v[4:19], v[108:111], v[100:103], v[4:19]
	s_add_i32 s11, s11, 1
	s_cmp_lt_u32 s11, 8
	s_cbranch_scc1 .Lg1k_loop
	s_nop 7
	s_nop 7

; __global__ void __launch_bounds__(256, 2) fwd_megakernel(Params p) {
;   cg::grid_group grid = cg::this_grid();
;   __shared__ __attribute__((aligned(16))) unsigned char smem[SMEM_BYTES];
;   __shared__ int s_item;
;   bf16* sA = (bf16*)smem;
;   bf16* sB = (bf16*)smem + 128 * LDT;
	.amdhsa_kernel _Z14fwd_megakernel6Params
		.amdhsa_group_segment_fixed_size 71744
		.amdhsa_private_segment_fixed_size 0
		.amdhsa_kernarg_size 664
		.amdhsa_user_sgpr_count 2
		.amdhsa_user_sgpr_dispatch_ptr 0
		.amdhsa_user_sgpr_queue_ptr 0
		.amdhsa_user_sgpr_kernarg_segment_ptr 1
		.amdhsa_user_sgpr_dispatch_id 0
		.amdhsa_user_sgpr_kernarg_preload_length 0
		.amdhsa_user_sgpr_kernarg_preload_offset 0
		.amdhsa_user_sgpr_private_segment_size 0
		.amdhsa_uses_dynamic_stack 0
		.amdhsa_enable_private_segment 0
		.amdhsa_system_sgpr_workgroup_id_x 1
		.amdhsa_system_sgpr_workgroup_id_y 0
		.amdhsa_system_sgpr_workgroup_id_z 0
		.amdhsa_system_sgpr_workgroup_info 0
		.amdhsa_system_vgpr_workitem_id 2
		.amdhsa_next_free_vgpr 256
		.amdhsa_next_free_sgpr 102
		.amdhsa_accum_offset 256
		.amdhsa_reserve_vcc 1
		.amdhsa_float_round_mode_32 0
		.amdhsa_float_round_mode_16_64 0
		.amdhsa_float_denorm_mode_32 3
		.amdhsa_float_denorm_mode_16_64 3
		.amdhsa_dx10_clamp 1
		.amdhsa_ieee_mode 1
		.amdhsa_fp16_overflow 0
		.amdhsa_tg_split 0
		.amdhsa_exception_fp_ieee_invalid_op 0
		.amdhsa_exception_fp_denorm_src 0
		.amdhsa_exception_fp_ieee_div_zero 0
		.amdhsa_exception_fp_ieee_overflow 0
		.amdhsa_exception_fp_ieee_underflow 0
		.amdhsa_exception_fp_ieee_inexact 0
		.amdhsa_exception_int_div_zero 0
	.end_amdhsa_kernel

; __global__ void __launch_bounds__(256, 2) fwd_megakernel(Params p) {
;   cg::grid_group grid = cg::this_grid();
;   __shared__ __attribute__((aligned(16))) unsigned char smem[SMEM_BYTES];
;   __shared__ int s_item;
;   bf16* sA = (bf16*)smem;
;   bf16* sB = (bf16*)smem + 128 * LDT;
amdhsa.kernels:
  - .agpr_count:     0
    .args:
      - .offset:         0
        .size:           408
        .value_kind:     by_value
      - .offset:         408
        .size:           4
        .value_kind:     hidden_block_count_x
      - .offset:         412
        .size:           4
        .value_kind:     hidden_block_count_y
      - .offset:         416
        .size:           4
        .value_kind:     hidden_block_count_z
      - .offset:         420
        .size:           2
        .value_kind:     hidden_group_size_x
      - .offset:         422
        .size:           2
        .value_kind:     hidden_group_size_y
      - .offset:         424
        .size:           2
        .value_kind:     hidden_group_size_z
      - .offset:         426
        .size:           2
        .value_kind:     hidden_remainder_x
      - .offset:         428
        .size:           2
        .value_kind:     hidden_remainder_y
      - .offset:         430
        .size:           2
        .value_kind:     hidden_remainder_z
      - .offset:         448
        .size:           8
        .value_kind:     hidden_global_offset_x
      - .offset:         456
        .size:           8
        .value_kind:     hidden_global_offset_y
      - .offset:         464
        .size:           8
        .value_kind:     hidden_global_offset_z
      - .offset:         472
        .size:           2
        .value_kind:     hidden_grid_dims
      - .offset:         496
        .size:           8
        .value_kind:     hidden_multigrid_sync_arg
    .group_segment_fixed_size: 71744
    .kernarg_segment_align: 8
    .kernarg_segment_size: 664
    .language:       OpenCL C
    .language_version:
      - 2
      - 0
    .max_flat_workgroup_size: 256
    .name:           _Z14fwd_megakernel6Params
    .private_segment_fixed_size: 0
    .sgpr_count:     108
    .sgpr_spill_count: 125
    .symbol:         _Z14fwd_megakernel6Params.kd
    .uniform_work_group_size: 1
    .uses_dynamic_stack: false
    .vgpr_count:     256
    .vgpr_spill_count: 0
    .wavefront_size: 64
